# speedup vs baseline: 1.0021x; 1.0021x over previous
; static __device__ __forceinline__ void attn_item(const Params& p, int head, int j, char* smraw) {
;     ...
;     float mx[2];
; #pragma unroll
;     for (int qt = 0; qt < 2; ++qt) {
;       float m = sacc[0][qt][0];
; #pragma unroll
;       for (int kt = 0; kt < 4; ++kt)
; #pragma unroll
;         for (int r = 0; r < 4; ++r) m = fmaxf(m, sacc[kt][qt][r]);
;       mx[qt] = max_x16_x32(m);
;     }
;     if (__any(first || mx[0] > THR || mx[1] > THR)) {
; #pragma unroll
;       for (int qt = 0; qt < 2; ++qt) {
;         const float d = first ? mx[qt] : fmaxf(mx[qt], 0.f);
;         const float alpha = first ? 1.f : __builtin_amdgcn_exp2f(-d);
;         mrun[qt] += d;
;         lrun[qt] *= alpha;
; #pragma unroll
;         for (int dt = 0; dt < 4; ++dt) oacc[dt][qt] = oacc[dt][qt] * alpha;
; #pragma unroll
;         for (int kt = 0; kt < 4; ++kt)
; #pragma unroll
;           for (int r = 0; r < 4; ++r) sacc[kt][qt][r] -= d;
;       }
.LBB0_378:
	ds_read_b128 v[100:103], v184
	ds_read_b128 v[104:107], v184 offset:4096
	ds_read_b128 v[108:111], v184 offset:8192
	ds_read_b128 v[112:115], v184 offset:12288
	ds_read_b128 v[116:119], v185
	ds_read_b128 v[120:123], v185 offset:4096
	ds_read_b128 v[124:127], v185 offset:8192
	ds_read_b128 v[156:159], v185 offset:12288
	ds_read_b128 v[160:163], v186
	ds_read_b128 v[164:167], v186 offset:4096
	ds_read_b128 v[168:171], v186 offset:8192
	ds_read_b128 v[192:195], v186 offset:12288
	s_cmp_eq_u32 s3, 3
	v_xor_b32_e32 v96, 0x80000000, v190
	s_cselect_b64 s[0:1], -1, 0
	v_mov_b32_e32 v97, v96
	v_mov_b32_e32 v98, v96
	v_mov_b32_e32 v99, v96
	v_xor_b32_e32 v196, 0x80000000, v189
	v_mov_b32_e32 v197, v196
	v_mov_b32_e32 v198, v196
	v_mov_b32_e32 v199, v196
	s_setprio 1
	s_waitcnt lgkmcnt(11)
	v_mfma_f32_16x16x32_bf16 v[200:203], v[100:103], v[0:3], v[96:99]
	v_mfma_f32_16x16x32_bf16 v[100:103], v[100:103], v[12:15], v[196:199]
	s_waitcnt lgkmcnt(10)
	v_mfma_f32_16x16x32_bf16 v[204:207], v[104:107], v[0:3], v[96:99]
	v_mfma_f32_16x16x32_bf16 v[104:107], v[104:107], v[12:15], v[196:199]
	s_waitcnt lgkmcnt(9)
	v_mfma_f32_16x16x32_bf16 v[208:211], v[108:111], v[0:3], v[96:99]
	v_mfma_f32_16x16x32_bf16 v[108:111], v[108:111], v[12:15], v[196:199]
	s_waitcnt lgkmcnt(8)
	v_mfma_f32_16x16x32_bf16 v[96:99], v[112:115], v[0:3], v[96:99]
	v_mfma_f32_16x16x32_bf16 v[112:115], v[112:115], v[12:15], v[196:199]
	s_waitcnt lgkmcnt(7)
	v_mfma_f32_16x16x32_bf16 v[196:199], v[116:119], v[4:7], v[200:203]
	v_mfma_f32_16x16x32_bf16 v[100:103], v[116:119], v[16:19], v[100:103]
	s_waitcnt lgkmcnt(6)
	v_mfma_f32_16x16x32_bf16 v[116:119], v[120:123], v[4:7], v[204:207]
	v_mfma_f32_16x16x32_bf16 v[104:107], v[120:123], v[16:19], v[104:107]
	s_waitcnt lgkmcnt(5)
	v_mfma_f32_16x16x32_bf16 v[200:203], v[124:127], v[4:7], v[208:211]
	v_mfma_f32_16x16x32_bf16 v[204:207], v[124:127], v[16:19], v[108:111]
	s_waitcnt lgkmcnt(4)
	v_mfma_f32_16x16x32_bf16 v[96:99], v[156:159], v[4:7], v[96:99]
	v_mfma_f32_16x16x32_bf16 v[156:159], v[156:159], v[16:19], v[112:115]
	s_waitcnt lgkmcnt(3)
	v_mfma_f32_16x16x32_bf16 v[124:127], v[160:163], v[8:11], v[196:199]
	v_mfma_f32_16x16x32_bf16 v[108:111], v[160:163], v[20:23], v[100:103]
	s_waitcnt lgkmcnt(2)
	v_mfma_f32_16x16x32_bf16 v[120:123], v[164:167], v[8:11], v[116:119]
	v_mfma_f32_16x16x32_bf16 v[104:107], v[164:167], v[20:23], v[104:107]
	s_waitcnt lgkmcnt(1)
	v_mfma_f32_16x16x32_bf16 v[116:119], v[168:171], v[8:11], v[200:203]
	v_mfma_f32_16x16x32_bf16 v[100:103], v[168:171], v[20:23], v[204:207]
	s_waitcnt lgkmcnt(0)
	v_mfma_f32_16x16x32_bf16 v[112:115], v[192:195], v[8:11], v[96:99]
	v_mfma_f32_16x16x32_bf16 v[96:99], v[192:195], v[20:23], v[156:159]
	s_setprio 0
	v_max3_f32 v128, v124, v125, v126
	v_max3_f32 v128, v128, v127, v120
	v_max3_f32 v156, v108, v109, v110
	v_max3_f32 v128, v128, v121, v122
	v_max3_f32 v156, v156, v111, v104
	v_max3_f32 v128, v128, v123, v116
	v_max3_f32 v156, v156, v105, v106
	v_max3_f32 v128, v128, v117, v118
	v_max3_f32 v156, v156, v107, v100
	v_max3_f32 v128, v128, v119, v112
	v_max3_f32 v156, v156, v101, v102
	v_max3_f32 v128, v128, v113, v114
	v_max3_f32 v156, v156, v103, v96
	v_max_f32_e32 v128, v128, v115
	v_max3_f32 v156, v156, v97, v98
	v_max_f32_e32 v156, v156, v99
	v_max_f32_e32 v157, v128, v156
	v_cmp_lt_f32_e32 vcc, s33, v157
	s_or_b64 vcc, s[0:1], vcc
	s_cbranch_vccz .LBB0_380
	v_mov_b32_e32 v157, v128
	s_nop 1
	v_permlane16_swap_b32_e32 v128, v157
	v_max_f32_e32 v157, v157, v157
	v_max_f32_e32 v128, v128, v128
	v_max_f32_e32 v128, v128, v157
	v_mov_b32_e32 v157, v128
	s_nop 1
	v_permlane32_swap_b32_e32 v128, v157
	v_max_f32_e32 v157, v157, v157
	v_max_f32_e32 v128, v128, v128
	v_max_f32_e32 v128, v128, v157
	v_mov_b32_e32 v157, v156
	s_nop 1
	v_permlane16_swap_b32_e32 v156, v157
	v_max_f32_e32 v157, v157, v157
	v_max_f32_e32 v156, v156, v156
	v_max_f32_e32 v156, v156, v157
	v_mov_b32_e32 v157, v156
	s_nop 1
	v_permlane32_swap_b32_e32 v156, v157
	v_max_f32_e32 v157, v157, v157
	v_max_f32_e32 v156, v156, v156
	v_max_f32_e32 v156, v156, v157
	v_max_f32_e32 v157, v128, v128
	v_max_f32_e32 v157, 0, v157
	v_max_f32_e32 v158, v156, v156
	v_cndmask_b32_e64 v128, v157, v128, s[0:1]
	v_max_f32_e32 v158, 0, v158
	v_exp_f32_e64 v157, -v128
	v_cndmask_b32_e64 v156, v158, v156, s[0:1]
	v_exp_f32_e64 v158, -v156
	v_add_f32_e32 v190, v190, v128
	v_cndmask_b32_e64 v159, v157, 1.0, s[0:1]
	v_pk_add_f32 v[124:125], v[124:125], v[128:129] op_sel_hi:[1,0] neg_lo:[0,1] neg_hi:[0,1]
	v_pk_add_f32 v[126:127], v[126:127], v[128:129] op_sel_hi:[1,0] neg_lo:[0,1] neg_hi:[0,1]
	v_pk_add_f32 v[120:121], v[120:121], v[128:129] op_sel_hi:[1,0] neg_lo:[0,1] neg_hi:[0,1]
	v_pk_add_f32 v[122:123], v[122:123], v[128:129] op_sel_hi:[1,0] neg_lo:[0,1] neg_hi:[0,1]
	v_pk_add_f32 v[116:117], v[116:117], v[128:129] op_sel_hi:[1,0] neg_lo:[0,1] neg_hi:[0,1]
	v_pk_add_f32 v[118:119], v[118:119], v[128:129] op_sel_hi:[1,0] neg_lo:[0,1] neg_hi:[0,1]
	v_pk_add_f32 v[112:113], v[112:113], v[128:129] op_sel_hi:[1,0] neg_lo:[0,1] neg_hi:[0,1]
	v_pk_add_f32 v[114:115], v[114:115], v[128:129] op_sel_hi:[1,0] neg_lo:[0,1] neg_hi:[0,1]
	v_cndmask_b32_e64 v158, v158, 1.0, s[0:1]
	v_mov_b32_e32 v128, v159
	v_pk_mul_f32 v[94:95], v[94:95], v[128:129] op_sel_hi:[1,0]
	v_pk_mul_f32 v[92:93], v[92:93], v[128:129] op_sel_hi:[1,0]
	v_pk_mul_f32 v[90:91], v[90:91], v[128:129] op_sel_hi:[1,0]
	v_pk_mul_f32 v[88:89], v[88:89], v[128:129] op_sel_hi:[1,0]
	v_pk_mul_f32 v[86:87], v[86:87], v[128:129] op_sel_hi:[1,0]
	v_pk_mul_f32 v[84:85], v[84:85], v[128:129] op_sel_hi:[1,0]
	v_pk_mul_f32 v[82:83], v[82:83], v[128:129] op_sel_hi:[1,0]
	v_pk_mul_f32 v[80:81], v[80:81], v[128:129] op_sel_hi:[1,0]
	v_add_f32_e32 v189, v189, v156
	v_pk_mul_f32 v[144:145], v[144:145], v[158:159]
	v_pk_mul_f32 v[78:79], v[78:79], v[158:159] op_sel_hi:[1,0]
	v_pk_mul_f32 v[76:77], v[76:77], v[158:159] op_sel_hi:[1,0]
	v_pk_mul_f32 v[74:75], v[74:75], v[158:159] op_sel_hi:[1,0]
	v_pk_mul_f32 v[72:73], v[72:73], v[158:159] op_sel_hi:[1,0]
	v_pk_mul_f32 v[70:71], v[70:71], v[158:159] op_sel_hi:[1,0]
	v_pk_mul_f32 v[68:69], v[68:69], v[158:159] op_sel_hi:[1,0]
	v_pk_mul_f32 v[66:67], v[66:67], v[158:159] op_sel_hi:[1,0]
	v_pk_mul_f32 v[64:65], v[64:65], v[158:159] op_sel_hi:[1,0]
	v_pk_add_f32 v[108:109], v[108:109], v[156:157] op_sel_hi:[1,0] neg_lo:[0,1] neg_hi:[0,1]
	v_pk_add_f32 v[110:111], v[110:111], v[156:157] op_sel_hi:[1,0] neg_lo:[0,1] neg_hi:[0,1]
	v_pk_add_f32 v[104:105], v[104:105], v[156:157] op_sel_hi:[1,0] neg_lo:[0,1] neg_hi:[0,1]
	v_pk_add_f32 v[106:107], v[106:107], v[156:157] op_sel_hi:[1,0] neg_lo:[0,1] neg_hi:[0,1]
	v_pk_add_f32 v[100:101], v[100:101], v[156:157] op_sel_hi:[1,0] neg_lo:[0,1] neg_hi:[0,1]
	v_pk_add_f32 v[102:103], v[102:103], v[156:157] op_sel_hi:[1,0] neg_lo:[0,1] neg_hi:[0,1]
	v_pk_add_f32 v[96:97], v[96:97], v[156:157] op_sel_hi:[1,0] neg_lo:[0,1] neg_hi:[0,1]
	v_pk_add_f32 v[98:99], v[98:99], v[156:157] op_sel_hi:[1,0] neg_lo:[0,1] neg_hi:[0,1]

; static __device__ __forceinline__ void attn_item(const Params& p, int head, int j, char* smraw) {
;     ...
;     float mx[2];
; #pragma unroll
;     for (int qt = 0; qt < 2; ++qt) {
;       float m = sacc[0][qt][0];
; #pragma unroll
;       for (int kt = 0; kt < 4; ++kt)
; #pragma unroll
;         for (int r = 0; r < 4; ++r) m = fmaxf(m, sacc[kt][qt][r]);
;       mx[qt] = max_x16_x32(m);
;     }
;     if (__any(first || mx[0] > THR || mx[1] > THR)) {
; #pragma unroll
;       for (int qt = 0; qt < 2; ++qt) {
;         const float d = first ? mx[qt] : fmaxf(mx[qt], 0.f);
;         const float alpha = first ? 1.f : __builtin_amdgcn_exp2f(-d);
;         mrun[qt] += d;
;         lrun[qt] *= alpha;
; #pragma unroll
;         for (int dt = 0; dt < 4; ++dt) oacc[dt][qt] = oacc[dt][qt] * alpha;
; #pragma unroll
;         for (int kt = 0; kt < 4; ++kt)
; #pragma unroll
;           for (int r = 0; r < 4; ++r) sacc[kt][qt][r] -= d;
;       }
.LBB0_382:
	v_xor_b32_e32 v166, 0x80000000, v189
	v_mov_b32_e32 v167, v166
	v_mov_b32_e32 v168, v166
	v_mov_b32_e32 v169, v166
	ds_read_b128 v[100:103], v184 offset:24576
	ds_read_b128 v[104:107], v184 offset:28672
	ds_read_b128 v[108:111], v184 offset:32768
	ds_read_b128 v[112:115], v184 offset:36864
	ds_read_b128 v[116:119], v185 offset:24576
	ds_read_b128 v[120:123], v185 offset:28672
	ds_read_b128 v[124:127], v185 offset:32768
	ds_read_b128 v[146:149], v185 offset:36864
	ds_read_b128 v[150:153], v186 offset:24576
	ds_read_b128 v[154:157], v186 offset:28672
	ds_read_b128 v[158:161], v186 offset:32768
	ds_read_b128 v[162:165], v186 offset:36864
	v_xor_b32_e32 v96, 0x80000000, v190
	v_mov_b32_e32 v97, v96
	v_mov_b32_e32 v98, v96
	v_mov_b32_e32 v99, v96
	s_setprio 1
	s_waitcnt lgkmcnt(11)
	v_mfma_f32_16x16x32_bf16 v[170:173], v[100:103], v[0:3], v[96:99]
	v_mfma_f32_16x16x32_bf16 v[100:103], v[100:103], v[12:15], v[166:169]
	s_waitcnt lgkmcnt(10)
	v_mfma_f32_16x16x32_bf16 v[192:195], v[104:107], v[0:3], v[96:99]
	v_mfma_f32_16x16x32_bf16 v[104:107], v[104:107], v[12:15], v[166:169]
	s_waitcnt lgkmcnt(9)
	v_mfma_f32_16x16x32_bf16 v[196:199], v[108:111], v[0:3], v[96:99]
	v_mfma_f32_16x16x32_bf16 v[108:111], v[108:111], v[12:15], v[166:169]
	s_waitcnt lgkmcnt(8)
	v_mfma_f32_16x16x32_bf16 v[96:99], v[112:115], v[0:3], v[96:99]
	v_mfma_f32_16x16x32_bf16 v[112:115], v[112:115], v[12:15], v[166:169]
	s_waitcnt lgkmcnt(7)
	v_mfma_f32_16x16x32_bf16 v[166:169], v[116:119], v[4:7], v[170:173]
	v_mfma_f32_16x16x32_bf16 v[100:103], v[116:119], v[16:19], v[100:103]
	s_waitcnt lgkmcnt(6)
	v_mfma_f32_16x16x32_bf16 v[116:119], v[120:123], v[4:7], v[192:195]
	v_mfma_f32_16x16x32_bf16 v[104:107], v[120:123], v[16:19], v[104:107]
	s_waitcnt lgkmcnt(5)
	v_mfma_f32_16x16x32_bf16 v[170:173], v[124:127], v[4:7], v[196:199]
	v_mfma_f32_16x16x32_bf16 v[192:195], v[124:127], v[16:19], v[108:111]
	s_waitcnt lgkmcnt(4)
	v_mfma_f32_16x16x32_bf16 v[96:99], v[146:149], v[4:7], v[96:99]
	v_mfma_f32_16x16x32_bf16 v[146:149], v[146:149], v[16:19], v[112:115]
	s_waitcnt lgkmcnt(3)
	v_mfma_f32_16x16x32_bf16 v[124:127], v[150:153], v[8:11], v[166:169]
	v_mfma_f32_16x16x32_bf16 v[108:111], v[150:153], v[20:23], v[100:103]
	s_waitcnt lgkmcnt(2)
	v_mfma_f32_16x16x32_bf16 v[120:123], v[154:157], v[8:11], v[116:119]
	v_mfma_f32_16x16x32_bf16 v[104:107], v[154:157], v[20:23], v[104:107]
	s_waitcnt lgkmcnt(1)
	v_mfma_f32_16x16x32_bf16 v[116:119], v[158:161], v[8:11], v[170:173]
	v_mfma_f32_16x16x32_bf16 v[100:103], v[158:161], v[20:23], v[192:195]
	s_waitcnt lgkmcnt(0)
	v_mfma_f32_16x16x32_bf16 v[112:115], v[162:165], v[8:11], v[96:99]
	v_mfma_f32_16x16x32_bf16 v[96:99], v[162:165], v[20:23], v[146:149]
	s_setprio 0
	v_max3_f32 v128, v108, v109, v110
	v_max3_f32 v128, v128, v111, v104
	v_max3_f32 v146, v124, v125, v126
	v_max3_f32 v128, v128, v105, v106
	v_max3_f32 v146, v146, v127, v120
	v_max3_f32 v128, v128, v107, v100
	v_max3_f32 v146, v146, v121, v122
	v_max3_f32 v128, v128, v101, v102
	v_max3_f32 v146, v146, v123, v116
	v_max3_f32 v128, v128, v103, v96
	v_max3_f32 v146, v146, v117, v118
	v_max3_f32 v128, v128, v97, v98
	v_max3_f32 v146, v146, v119, v112
	v_max_f32_e32 v128, v128, v99
	v_max3_f32 v146, v146, v113, v114
	v_max_f32_e32 v146, v146, v115
	v_max_f32_e32 v147, v146, v128
	v_cmp_lt_f32_e32 vcc, s33, v147
	s_cbranch_vccz .LBB0_384
	v_mov_b32_e32 v147, v146
	s_nop 1
	v_permlane16_swap_b32_e32 v146, v147
	v_max_f32_e32 v147, v147, v147
	v_max_f32_e32 v146, v146, v146
	v_max_f32_e32 v146, v146, v147
	v_mov_b32_e32 v147, v146
	s_nop 1
	v_permlane32_swap_b32_e32 v146, v147
	v_max_f32_e32 v147, v147, v147
	v_max_f32_e32 v146, v146, v146
	v_max_f32_e32 v146, v146, v147
	v_mov_b32_e32 v147, v128
	s_nop 1
	v_permlane16_swap_b32_e32 v128, v147
	v_max_f32_e32 v147, v147, v147
	v_max_f32_e32 v128, v128, v128
	v_max_f32_e32 v128, v128, v147
	v_mov_b32_e32 v147, v128
	s_nop 1
	v_permlane32_swap_b32_e32 v128, v147
	v_max_f32_e32 v147, v147, v147
	v_max_f32_e32 v128, v128, v128
	v_max_f32_e32 v128, v128, v147
	v_max_f32_e32 v146, v146, v146
	v_max_f32_e32 v146, 0, v146
	v_max_f32_e32 v128, v128, v128
	v_exp_f32_e64 v148, -v146
	v_max_f32_e32 v128, 0, v128
	v_exp_f32_e64 v150, -v128
	v_add_f32_e32 v190, v190, v146
	v_mov_b32_e32 v151, v148
	v_pk_mul_f32 v[94:95], v[94:95], v[148:149] op_sel_hi:[1,0]
	v_pk_mul_f32 v[92:93], v[92:93], v[148:149] op_sel_hi:[1,0]
	v_pk_mul_f32 v[86:87], v[86:87], v[148:149] op_sel_hi:[1,0]
	v_pk_mul_f32 v[84:85], v[84:85], v[148:149] op_sel_hi:[1,0]
	v_pk_mul_f32 v[78:79], v[78:79], v[148:149] op_sel_hi:[1,0]
	v_pk_mul_f32 v[76:77], v[76:77], v[148:149] op_sel_hi:[1,0]
	v_pk_mul_f32 v[70:71], v[70:71], v[148:149] op_sel_hi:[1,0]
	v_pk_mul_f32 v[68:69], v[68:69], v[148:149] op_sel_hi:[1,0]
	v_pk_add_f32 v[124:125], v[124:125], v[146:147] op_sel_hi:[1,0] neg_lo:[0,1] neg_hi:[0,1]
	v_pk_add_f32 v[126:127], v[126:127], v[146:147] op_sel_hi:[1,0] neg_lo:[0,1] neg_hi:[0,1]
	v_pk_add_f32 v[120:121], v[120:121], v[146:147] op_sel_hi:[1,0] neg_lo:[0,1] neg_hi:[0,1]
	v_pk_add_f32 v[122:123], v[122:123], v[146:147] op_sel_hi:[1,0] neg_lo:[0,1] neg_hi:[0,1]
	v_pk_add_f32 v[116:117], v[116:117], v[146:147] op_sel_hi:[1,0] neg_lo:[0,1] neg_hi:[0,1]
	v_pk_add_f32 v[118:119], v[118:119], v[146:147] op_sel_hi:[1,0] neg_lo:[0,1] neg_hi:[0,1]
	v_pk_add_f32 v[112:113], v[112:113], v[146:147] op_sel_hi:[1,0] neg_lo:[0,1] neg_hi:[0,1]
	v_pk_add_f32 v[114:115], v[114:115], v[146:147] op_sel_hi:[1,0] neg_lo:[0,1] neg_hi:[0,1]
	v_add_f32_e32 v189, v189, v128
	v_pk_mul_f32 v[144:145], v[144:145], v[150:151]
	v_pk_mul_f32 v[90:91], v[90:91], v[150:151] op_sel_hi:[1,0]
	v_pk_mul_f32 v[88:89], v[88:89], v[150:151] op_sel_hi:[1,0]
	v_pk_mul_f32 v[82:83], v[82:83], v[150:151] op_sel_hi:[1,0]
	v_pk_mul_f32 v[80:81], v[80:81], v[150:151] op_sel_hi:[1,0]
	v_pk_mul_f32 v[74:75], v[74:75], v[150:151] op_sel_hi:[1,0]
	v_pk_mul_f32 v[72:73], v[72:73], v[150:151] op_sel_hi:[1,0]
	v_pk_mul_f32 v[66:67], v[66:67], v[150:151] op_sel_hi:[1,0]
	v_pk_mul_f32 v[64:65], v[64:65], v[150:151] op_sel_hi:[1,0]
	v_pk_add_f32 v[108:109], v[108:109], v[128:129] op_sel_hi:[1,0] neg_lo:[0,1] neg_hi:[0,1]
	v_pk_add_f32 v[110:111], v[110:111], v[128:129] op_sel_hi:[1,0] neg_lo:[0,1] neg_hi:[0,1]
	v_pk_add_f32 v[104:105], v[104:105], v[128:129] op_sel_hi:[1,0] neg_lo:[0,1] neg_hi:[0,1]
	v_pk_add_f32 v[106:107], v[106:107], v[128:129] op_sel_hi:[1,0] neg_lo:[0,1] neg_hi:[0,1]
	v_pk_add_f32 v[100:101], v[100:101], v[128:129] op_sel_hi:[1,0] neg_lo:[0,1] neg_hi:[0,1]
	v_pk_add_f32 v[102:103], v[102:103], v[128:129] op_sel_hi:[1,0] neg_lo:[0,1] neg_hi:[0,1]
	v_pk_add_f32 v[96:97], v[96:97], v[128:129] op_sel_hi:[1,0] neg_lo:[0,1] neg_hi:[0,1]
	v_pk_add_f32 v[98:99], v[98:99], v[128:129] op_sel_hi:[1,0] neg_lo:[0,1] neg_hi:[0,1]
